# out-projection GEMM k-loops: E-half address arithmetic hoisted above the head barrier (temps renamed), on top of v_rot2
# baseline (speedup 1.0000x reference)
.LBB0_560:
	s_ashr_i32 s22, s30, 3
	s_lshr_b32 s24, s22, 29
	s_add_i32 s24, s22, s24
	s_and_b32 s25, s24, 0x1fffff8
	s_sub_i32 s22, s22, s25
	s_lshl_b32 s24, s24, 8
	s_lshl_b32 s25, s30, 8
	s_and_b32 s24, s24, 0xfffff800
	s_and_b32 s25, s25, 0x700
	s_or_b32 s28, s24, s25
	s_ashr_i32 s29, s28, 31
	s_lshl_b32 s24, s22, 7
	s_lshl_b64 s[34:35], s[28:29], 12
	s_add_u32 s34, s3, s34
	s_addc_u32 s35, s4, s35
	s_ashr_i32 s25, s24, 31
	v_mov_b32_e32 v36, v220
	s_lshl_b64 s[36:37], s[24:25], 12
	s_add_u32 s36, s5, s36
	v_ashrrev_i32_e32 v26, 2, v36
	v_ashrrev_i32_e32 v27, 31, v26
	s_addc_u32 s37, s8, s37
	v_lshlrev_b64 v[0:1], 12, v[26:27]
	v_lshlrev_b32_e32 v4, 4, v36
	v_lshl_add_u64 v[2:3], s[36:37], 0, v[0:1]
	v_lshl_add_u64 v[0:1], s[34:35], 0, v[0:1]
	v_and_b32_e32 v176, 48, v4
	s_waitcnt vmcnt(9)
	v_lshl_add_u64 v[152:153], v[0:1], 0, v[176:177]
	v_add_co_u32_e32 v28, vcc, s9, v152
	v_lshl_add_u64 v[154:155], v[2:3], 0, v[176:177]
	s_nop 0
	v_addc_co_u32_e32 v29, vcc, 0, v153, vcc
	v_add_co_u32_e32 v30, vcc, s26, v152
	global_load_dwordx4 v[2:5], v[152:153], off
	s_nop 0
	v_addc_co_u32_e32 v31, vcc, 0, v153, vcc
	v_add_co_u32_e32 v32, vcc, s27, v152
	global_load_dwordx4 v[6:9], v[28:29], off
	s_nop 0
	v_addc_co_u32_e32 v33, vcc, 0, v153, vcc
	v_add_co_u32_e32 v34, vcc, s9, v154
	global_load_dwordx4 v[10:13], v[30:31], off
	s_nop 0
	v_addc_co_u32_e32 v35, vcc, 0, v155, vcc
	global_load_dwordx4 v[14:17], v[32:33], off
	global_load_dwordx4 v[18:21], v[154:155], off
	global_load_dwordx4 v[22:25], v[34:35], off
	global_load_dwordx4 v[112:115], v[152:153], off offset:64
	global_load_dwordx4 v[120:123], v[28:29], off offset:64
	global_load_dwordx4 v[124:127], v[30:31], off offset:64
	global_load_dwordx4 v[128:131], v[32:33], off offset:64
	global_load_dwordx4 v[116:119], v[154:155], off offset:64
	global_load_dwordx4 v[132:135], v[34:35], off offset:64
	v_lshrrev_b32_e32 v27, 4, v36
	v_lshrrev_b32_e32 v37, 2, v36
	v_sub_u32_e32 v40, 0, v27
	v_sub_u32_e32 v37, 0, v37
	v_and_b32_e32 v38, 0x3ffff8f, v36
	v_lshlrev_b32_e32 v39, 6, v36
	v_xor_b32_e32 v36, v36, v40
	v_xor_b32_e32 v27, v27, v37
	v_lshlrev_b32_e32 v36, 4, v36
	v_lshlrev_b32_e32 v27, 4, v27
	v_and_b32_e32 v41, 0x1000, v39
	v_and_b32_e32 v36, 48, v36
	v_and_b32_e32 v27, 48, v27
	v_and_b32_e32 v42, 0x3c0, v39
	v_and_b32_e32 v39, 0xffffe3c0, v39
	v_lshl_add_u32 v38, v38, 6, v196
	v_lshl_or_b32 v164, v26, 6, v36
	v_or_b32_e32 v26, v27, v41
	s_mov_b32 s25, -2
	s_mov_b32 s29, s23
	v_mov_b32_e32 v0, 0
	v_mov_b32_e32 v1, v177
	v_or3_b32 v165, v41, v42, v27
	v_add_u32_e32 v166, v27, v39
	v_add_u32_e32 v167, v27, v38
	v_add_u32_e32 v168, v26, v42
	v_lshl_add_u64 v[156:157], v[152:153], 0, s[12:13]
	v_lshl_add_u64 v[158:159], v[152:153], 0, s[14:15]
	v_lshl_add_u64 v[160:161], v[152:153], 0, s[16:17]
	v_lshl_add_u64 v[162:163], v[154:155], 0, s[12:13]
	v_mov_b32_e32 v26, v177
	v_mov_b32_e32 v27, v177
	v_mov_b32_e32 v28, 0
	v_mov_b32_e32 v29, v177
	v_mov_b32_e32 v30, v177
	v_mov_b32_e32 v31, v177
	v_mov_b32_e32 v32, 0
	v_mov_b32_e32 v33, v177
	v_mov_b32_e32 v34, v177
	v_mov_b32_e32 v35, v177
	v_mov_b32_e32 v36, 0
	v_mov_b32_e32 v37, v177
	v_mov_b32_e32 v38, v177
	v_mov_b32_e32 v39, v177
	v_mov_b32_e32 v40, 0
	v_mov_b32_e32 v41, v177
	v_mov_b32_e32 v42, v177
	v_mov_b32_e32 v43, v177
	v_mov_b32_e32 v44, 0
	s_waitcnt vmcnt(11)
	ds_write_b128 v164, v[2:5]
	s_waitcnt vmcnt(10)
	ds_write_b128 v164, v[6:9] offset:4096
	s_waitcnt vmcnt(9)
	ds_write_b128 v164, v[10:13] offset:8192
	s_waitcnt vmcnt(8)
	ds_write_b128 v164, v[14:17] offset:12288
	s_waitcnt vmcnt(7)
	ds_write_b128 v164, v[18:21] offset:32768
	s_waitcnt vmcnt(6)
	ds_write_b128 v164, v[22:25] offset:36864
	v_mov_b32_e32 v2, v177
	v_mov_b32_e32 v3, v177
	v_mov_b32_e32 v4, 0
	v_mov_b32_e32 v5, v177
	v_mov_b32_e32 v6, v177
	v_mov_b32_e32 v7, v177
	v_mov_b32_e32 v8, 0
	v_mov_b32_e32 v9, v177
	v_mov_b32_e32 v10, v177
	v_mov_b32_e32 v11, v177
	v_mov_b32_e32 v12, 0
	v_mov_b32_e32 v13, v177
	v_mov_b32_e32 v14, v177
	v_mov_b32_e32 v15, v177
	v_mov_b32_e32 v16, 0
	v_mov_b32_e32 v17, v177
	v_mov_b32_e32 v18, v177
	v_mov_b32_e32 v19, v177
	v_mov_b32_e32 v20, 0
	v_mov_b32_e32 v21, v177
	v_mov_b32_e32 v22, v177
	v_mov_b32_e32 v23, v177
	v_mov_b32_e32 v24, 0
	v_mov_b32_e32 v25, v177
	v_mov_b32_e32 v45, v177
	v_mov_b32_e32 v46, v177
	v_mov_b32_e32 v47, v177
	v_mov_b32_e32 v48, 0
	v_mov_b32_e32 v49, v177
	v_mov_b32_e32 v50, v177
	v_mov_b32_e32 v51, v177
	v_mov_b32_e32 v52, 0
	v_mov_b32_e32 v53, v177
	v_mov_b32_e32 v54, v177
	v_mov_b32_e32 v55, v177
	v_mov_b32_e32 v56, 0
	v_mov_b32_e32 v57, v177
	v_mov_b32_e32 v58, v177
	v_mov_b32_e32 v59, v177
	v_mov_b32_e32 v60, 0
	v_mov_b32_e32 v61, v177
	v_mov_b32_e32 v62, v177
	v_mov_b32_e32 v63, v177
	v_mov_b32_e32 v64, 0
	v_mov_b32_e32 v65, v177
	v_mov_b32_e32 v66, v177
	v_mov_b32_e32 v67, v177
	v_mov_b32_e32 v68, 0
	v_mov_b32_e32 v69, v177
	v_mov_b32_e32 v70, v177
	v_mov_b32_e32 v71, v177
	v_mov_b32_e32 v72, 0
	v_mov_b32_e32 v73, v177
	v_mov_b32_e32 v74, v177
	v_mov_b32_e32 v75, v177
	v_mov_b32_e32 v76, 0
	v_mov_b32_e32 v77, v177
	v_mov_b32_e32 v78, v177
	v_mov_b32_e32 v79, v177
	v_mov_b32_e32 v80, 0
	v_mov_b32_e32 v81, v177
	v_mov_b32_e32 v82, v177
	v_mov_b32_e32 v83, v177
	v_mov_b32_e32 v84, 0
	v_mov_b32_e32 v85, v177
	v_mov_b32_e32 v86, v177
	v_mov_b32_e32 v87, v177
	v_mov_b32_e32 v88, 0
	v_mov_b32_e32 v89, v177
	v_mov_b32_e32 v90, v177
	v_mov_b32_e32 v91, v177
	v_mov_b32_e32 v92, 0
	v_mov_b32_e32 v93, v177
	v_mov_b32_e32 v94, v177
	v_mov_b32_e32 v95, v177
	v_mov_b32_e32 v96, 0
	v_mov_b32_e32 v97, v177
	v_mov_b32_e32 v98, v177
	v_mov_b32_e32 v99, v177
	v_mov_b32_e32 v100, 0
	v_mov_b32_e32 v101, v177
	v_mov_b32_e32 v102, v177
	v_mov_b32_e32 v103, v177
	v_mov_b32_e32 v104, 0
	v_mov_b32_e32 v105, v177
	v_mov_b32_e32 v106, v177
	v_mov_b32_e32 v107, v177
	v_mov_b32_e32 v108, 0
	v_mov_b32_e32 v109, v177
	v_mov_b32_e32 v110, v177
	v_mov_b32_e32 v111, v177
	v_mov_b32_e32 v136, 0
	v_mov_b32_e32 v137, v177
	v_mov_b32_e32 v138, v177
	v_mov_b32_e32 v139, v177
	v_mov_b32_e32 v140, 0
	v_mov_b32_e32 v141, v177
	v_mov_b32_e32 v142, v177
	v_mov_b32_e32 v143, v177
	v_mov_b32_e32 v144, 0
	v_mov_b32_e32 v145, v177
	v_mov_b32_e32 v146, v177
	v_mov_b32_e32 v147, v177
	v_mov_b32_e32 v148, 0
	v_mov_b32_e32 v149, v177
	v_mov_b32_e32 v150, v177
	v_mov_b32_e32 v151, v177
	s_waitcnt lgkmcnt(0)
	s_add_i32 s31, s29, 64
	s_min_u32 s22, s31, 0x7e0
	s_lshl_b32 s22, s22, 1
	v_lshl_add_u64 v[178:179], v[156:157], 0, s[22:23]
	v_lshl_add_u64 v[182:183], v[158:159], 0, s[22:23]
	v_lshl_add_u64 v[170:171], v[152:153], 0, s[22:23]
	v_lshl_add_u64 v[186:187], v[160:161], 0, s[22:23]
	v_lshl_add_u64 v[190:191], v[154:155], 0, s[22:23]
	v_lshl_add_u64 v[198:199], v[162:163], 0, s[22:23]

.LBB0_561:
	global_load_dwordx4 v[178:181], v[178:179], off
	global_load_dwordx4 v[182:185], v[182:183], off
	global_load_dwordx4 v[170:173], v[170:171], off
	ds_read_b128 v[202:205], v168 offset:32768
	global_load_dwordx4 v[186:189], v[186:187], off
	ds_read_b128 v[206:209], v168 offset:33792
	global_load_dwordx4 v[190:193], v[190:191], off
	global_load_dwordx4 v[198:201], v[198:199], off
	ds_read_b128 v[210:213], v168 offset:34816
	ds_read_b128 v[214:217], v168 offset:35840
	ds_read_b128 v[222:225], v166
	ds_read_b128 v[226:229], v166 offset:1024
	ds_read_b128 v[230:233], v166 offset:2048
	ds_read_b128 v[234:237], v166 offset:3072
	ds_read_b128 v[238:241], v166 offset:4096
	ds_read_b128 v[242:245], v166 offset:5120
	ds_read_b128 v[246:249], v166 offset:6144
	ds_read_b128 v[250:253], v166 offset:7168
	s_setprio 1
	s_waitcnt lgkmcnt(7)
	v_mfma_f32_16x16x32_bf16 v[148:151], v[202:205], v[222:225], v[148:151]
	v_mfma_f32_16x16x32_bf16 v[144:147], v[206:209], v[222:225], v[144:147]
	v_mfma_f32_16x16x32_bf16 v[140:143], v[210:213], v[222:225], v[140:143]
	v_mfma_f32_16x16x32_bf16 v[136:139], v[214:217], v[222:225], v[136:139]
	s_waitcnt vmcnt(11)
	ds_write_b128 v164, v[112:115] offset:16384
	s_waitcnt lgkmcnt(7)
	v_mfma_f32_16x16x32_bf16 v[108:111], v[202:205], v[226:229], v[108:111]
	v_mfma_f32_16x16x32_bf16 v[104:107], v[206:209], v[226:229], v[104:107]
	v_mfma_f32_16x16x32_bf16 v[100:103], v[210:213], v[226:229], v[100:103]
	v_mfma_f32_16x16x32_bf16 v[96:99], v[214:217], v[226:229], v[96:99]
	s_waitcnt vmcnt(9)
	ds_write_b128 v164, v[120:123] offset:20480
	s_waitcnt lgkmcnt(7)
	v_mfma_f32_16x16x32_bf16 v[92:95], v[202:205], v[230:233], v[92:95]
	v_mfma_f32_16x16x32_bf16 v[88:91], v[206:209], v[230:233], v[88:91]
	v_mfma_f32_16x16x32_bf16 v[84:87], v[210:213], v[230:233], v[84:87]
	v_mfma_f32_16x16x32_bf16 v[80:83], v[214:217], v[230:233], v[80:83]
	s_waitcnt vmcnt(8)
	ds_write_b128 v164, v[124:127] offset:24576
	s_waitcnt lgkmcnt(7)
	v_mfma_f32_16x16x32_bf16 v[76:79], v[202:205], v[234:237], v[76:79]
	v_mfma_f32_16x16x32_bf16 v[72:75], v[206:209], v[234:237], v[72:75]
	v_mfma_f32_16x16x32_bf16 v[68:71], v[210:213], v[234:237], v[68:71]
	v_mfma_f32_16x16x32_bf16 v[64:67], v[214:217], v[234:237], v[64:67]
	s_waitcnt vmcnt(7)
	ds_write_b128 v164, v[128:131] offset:28672
	s_waitcnt lgkmcnt(7)
	v_mfma_f32_16x16x32_bf16 v[60:63], v[202:205], v[238:241], v[60:63]
	v_mfma_f32_16x16x32_bf16 v[56:59], v[206:209], v[238:241], v[56:59]
	v_mfma_f32_16x16x32_bf16 v[52:55], v[210:213], v[238:241], v[52:55]
	v_mfma_f32_16x16x32_bf16 v[48:51], v[214:217], v[238:241], v[48:51]
	s_waitcnt vmcnt(7)
	ds_write_b128 v164, v[116:119] offset:40960
	s_waitcnt lgkmcnt(7)
	v_mfma_f32_16x16x32_bf16 v[44:47], v[202:205], v[242:245], v[44:47]
	v_mfma_f32_16x16x32_bf16 v[40:43], v[206:209], v[242:245], v[40:43]
	v_mfma_f32_16x16x32_bf16 v[36:39], v[210:213], v[242:245], v[36:39]
	v_mfma_f32_16x16x32_bf16 v[32:35], v[214:217], v[242:245], v[32:35]
	s_waitcnt vmcnt(6)
	ds_write_b128 v164, v[132:135] offset:45056
	s_waitcnt lgkmcnt(7)
	v_mfma_f32_16x16x32_bf16 v[28:31], v[202:205], v[246:249], v[28:31]
	v_mfma_f32_16x16x32_bf16 v[24:27], v[206:209], v[246:249], v[24:27]
	v_mfma_f32_16x16x32_bf16 v[20:23], v[210:213], v[246:249], v[20:23]
	v_mfma_f32_16x16x32_bf16 v[16:19], v[214:217], v[246:249], v[16:19]
	s_waitcnt lgkmcnt(6)
	v_mfma_f32_16x16x32_bf16 v[12:15], v[202:205], v[250:253], v[12:15]
	v_mfma_f32_16x16x32_bf16 v[8:11], v[206:209], v[250:253], v[8:11]
	v_mfma_f32_16x16x32_bf16 v[4:7], v[210:213], v[250:253], v[4:7]
	v_mfma_f32_16x16x32_bf16 v[0:3], v[214:217], v[250:253], v[0:3]
	s_setprio 0
	s_min_u32 s22, s29, 0x780
	s_lshl_b32 s22, s22, 1
	s_mov_b32 s35, s23
	s_add_i32 s34, s22, 0xc0
	v_lshl_add_u64 v[112:113], v[152:153], 0, s[22:23]
	v_lshl_add_u64 v[116:117], v[154:155], 0, s[22:23]
	v_lshl_add_u64 v[120:121], v[156:157], 0, s[34:35]
	v_lshl_add_u64 v[124:125], v[158:159], 0, s[34:35]
	v_lshl_add_u64 v[128:129], v[160:161], 0, s[34:35]
	v_lshl_add_u64 v[132:133], v[162:163], 0, s[34:35]
	s_waitcnt lgkmcnt(0)
	s_barrier
	global_load_dwordx4 v[112:115], v[112:113], off offset:192
	ds_read_b128 v[202:205], v165 offset:40960
	global_load_dwordx4 v[116:119], v[116:117], off offset:192
	ds_read_b128 v[206:209], v165 offset:41984
	global_load_dwordx4 v[120:123], v[120:121], off
	ds_read_b128 v[210:213], v165 offset:43008
	global_load_dwordx4 v[124:127], v[124:125], off
	ds_read_b128 v[214:217], v165 offset:44032
	global_load_dwordx4 v[128:131], v[128:129], off
	ds_read_b128 v[222:225], v167
	global_load_dwordx4 v[132:135], v[132:133], off
	ds_read_b128 v[226:229], v167 offset:1024
	ds_read_b128 v[230:233], v167 offset:2048
	ds_read_b128 v[234:237], v167 offset:3072
	ds_read_b128 v[238:241], v167 offset:4096
	ds_read_b128 v[242:245], v167 offset:5120
	ds_read_b128 v[246:249], v167 offset:6144
	ds_read_b128 v[250:253], v167 offset:7168
	s_setprio 1
	s_waitcnt lgkmcnt(7)
	v_mfma_f32_16x16x32_bf16 v[148:151], v[202:205], v[222:225], v[148:151]
	v_mfma_f32_16x16x32_bf16 v[144:147], v[206:209], v[222:225], v[144:147]
	v_mfma_f32_16x16x32_bf16 v[140:143], v[210:213], v[222:225], v[140:143]
	v_mfma_f32_16x16x32_bf16 v[136:139], v[214:217], v[222:225], v[136:139]
	s_waitcnt vmcnt(9)
	ds_write_b128 v164, v[170:173]
	s_waitcnt lgkmcnt(7)
	v_mfma_f32_16x16x32_bf16 v[108:111], v[202:205], v[226:229], v[108:111]
	v_mfma_f32_16x16x32_bf16 v[104:107], v[206:209], v[226:229], v[104:107]
	v_mfma_f32_16x16x32_bf16 v[100:103], v[210:213], v[226:229], v[100:103]
	v_mfma_f32_16x16x32_bf16 v[96:99], v[214:217], v[226:229], v[96:99]
	ds_write_b128 v164, v[178:181] offset:4096
	s_waitcnt lgkmcnt(7)
	v_mfma_f32_16x16x32_bf16 v[92:95], v[202:205], v[230:233], v[92:95]
	v_mfma_f32_16x16x32_bf16 v[88:91], v[206:209], v[230:233], v[88:91]
	v_mfma_f32_16x16x32_bf16 v[84:87], v[210:213], v[230:233], v[84:87]
	v_mfma_f32_16x16x32_bf16 v[80:83], v[214:217], v[230:233], v[80:83]
	ds_write_b128 v164, v[182:185] offset:8192
	s_waitcnt lgkmcnt(7)
	v_mfma_f32_16x16x32_bf16 v[76:79], v[202:205], v[234:237], v[76:79]
	v_mfma_f32_16x16x32_bf16 v[72:75], v[206:209], v[234:237], v[72:75]
	v_mfma_f32_16x16x32_bf16 v[68:71], v[210:213], v[234:237], v[68:71]
	v_mfma_f32_16x16x32_bf16 v[64:67], v[214:217], v[234:237], v[64:67]
	s_waitcnt vmcnt(8)
	ds_write_b128 v164, v[186:189] offset:12288
	s_waitcnt lgkmcnt(7)
	v_mfma_f32_16x16x32_bf16 v[60:63], v[202:205], v[238:241], v[60:63]
	v_mfma_f32_16x16x32_bf16 v[56:59], v[206:209], v[238:241], v[56:59]
	v_mfma_f32_16x16x32_bf16 v[52:55], v[210:213], v[238:241], v[52:55]
	v_mfma_f32_16x16x32_bf16 v[48:51], v[214:217], v[238:241], v[48:51]
	s_waitcnt vmcnt(7)
	ds_write_b128 v164, v[190:193] offset:32768
	s_waitcnt lgkmcnt(7)
	v_mfma_f32_16x16x32_bf16 v[44:47], v[202:205], v[242:245], v[44:47]
	v_mfma_f32_16x16x32_bf16 v[40:43], v[206:209], v[242:245], v[40:43]
	v_mfma_f32_16x16x32_bf16 v[36:39], v[210:213], v[242:245], v[36:39]
	v_mfma_f32_16x16x32_bf16 v[32:35], v[214:217], v[242:245], v[32:35]
	s_waitcnt vmcnt(6)
	ds_write_b128 v164, v[198:201] offset:36864
	s_waitcnt lgkmcnt(7)
	v_mfma_f32_16x16x32_bf16 v[28:31], v[202:205], v[246:249], v[28:31]
	v_mfma_f32_16x16x32_bf16 v[24:27], v[206:209], v[246:249], v[24:27]
	v_mfma_f32_16x16x32_bf16 v[20:23], v[210:213], v[246:249], v[20:23]
	v_mfma_f32_16x16x32_bf16 v[16:19], v[214:217], v[246:249], v[16:19]
	s_waitcnt lgkmcnt(6)
	v_mfma_f32_16x16x32_bf16 v[12:15], v[202:205], v[250:253], v[12:15]
	v_mfma_f32_16x16x32_bf16 v[8:11], v[206:209], v[250:253], v[8:11]
	v_mfma_f32_16x16x32_bf16 v[4:7], v[210:213], v[250:253], v[4:7]
	v_mfma_f32_16x16x32_bf16 v[0:3], v[214:217], v[250:253], v[0:3]
	s_setprio 0
	s_add_i32 s25, s25, 2
	s_mov_b32 s29, s31
	s_add_i32 s31, s29, 64
	s_min_u32 s22, s31, 0x7e0
	s_lshl_b32 s22, s22, 1
	v_lshl_add_u64 v[178:179], v[156:157], 0, s[22:23]
	v_lshl_add_u64 v[182:183], v[158:159], 0, s[22:23]
	v_lshl_add_u64 v[170:171], v[152:153], 0, s[22:23]
	v_lshl_add_u64 v[186:187], v[160:161], 0, s[22:23]
	v_lshl_add_u64 v[190:191], v[154:155], 0, s[22:23]
	v_lshl_add_u64 v[198:199], v[162:163], 0, s[22:23]
	s_cmp_lt_u32 s25, 62
	s_waitcnt lgkmcnt(0)
	s_cbranch_scc1 .Lrot2_4
	s_barrier
	s_waitcnt vmcnt(5)
	v_mov_b32_e32 v112, v220
	v_readlane_b32 s36, v254, 6
	v_and_b32_e32 v114, 0xffffff80, v112
	v_bfe_u32 v176, v112, 4, 2
	v_add_u32_e32 v114, s28, v114
	v_and_b32_e32 v113, 64, v112
	v_and_or_b32 v180, v112, 15, v114
	v_lshlrev_b32_e32 v112, 2, v176
	v_or3_b32 v178, v112, v113, s24
	v_ashrrev_i32_e32 v179, 31, v178
	v_lshlrev_b64 v[214:215], 2, v[178:179]
	v_readlane_b32 s37, v254, 7
	v_ashrrev_i32_e32 v181, 31, v180
	v_or_b32_e32 v190, 16, v180
	v_lshl_add_u64 v[182:183], s[36:37], 0, v[214:215]
	v_lshlrev_b64 v[216:217], 12, v[180:181]
	v_ashrrev_i32_e32 v191, 31, v190
	v_or_b32_e32 v186, 32, v180
	v_lshl_add_u64 v[112:113], v[182:183], 0, v[216:217]
	v_lshlrev_b64 v[194:195], 12, v[190:191]
	v_ashrrev_i32_e32 v187, 31, v186
	v_or_b32_e32 v184, 48, v180
	global_load_dwordx4 v[198:201], v[112:113], off nt
	global_load_dwordx4 v[202:205], v[112:113], off offset:64 nt
	global_load_dwordx4 v[206:209], v[112:113], off offset:128 nt
	global_load_dwordx4 v[210:213], v[112:113], off offset:192 nt
	v_lshl_add_u64 v[112:113], v[182:183], 0, v[194:195]
	v_lshlrev_b64 v[192:193], 12, v[186:187]
	v_ashrrev_i32_e32 v185, 31, v184
	global_load_dwordx4 v[172:175], v[112:113], off nt
	global_load_dwordx4 v[168:171], v[112:113], off offset:64 nt
	global_load_dwordx4 v[164:167], v[112:113], off offset:128 nt
	global_load_dwordx4 v[160:163], v[112:113], off offset:192 nt
	v_lshl_add_u64 v[112:113], v[182:183], 0, v[192:193]
	v_lshlrev_b64 v[188:189], 12, v[184:185]
	global_load_dwordx4 v[156:159], v[112:113], off nt
	global_load_dwordx4 v[152:155], v[112:113], off offset:64 nt
	global_load_dwordx4 v[132:135], v[112:113], off offset:128 nt
	global_load_dwordx4 v[128:131], v[112:113], off offset:192 nt
	v_lshl_add_u64 v[112:113], v[182:183], 0, v[188:189]
	global_load_dwordx4 v[124:127], v[112:113], off nt
	global_load_dwordx4 v[120:123], v[112:113], off offset:64 nt
	global_load_dwordx4 v[116:119], v[112:113], off offset:128 nt
	s_nop 0
	global_load_dwordx4 v[112:115], v[112:113], off offset:192 nt
	v_cmp_eq_u32_e32 vcc, 0, v176
	v_readlane_b32 s38, v254, 8
	v_readlane_b32 s39, v254, 9
	v_readlane_b32 s40, v254, 10
	v_readlane_b32 s41, v254, 11
	v_readlane_b32 s42, v254, 12
	v_readlane_b32 s43, v254, 13
	v_readlane_b32 s44, v254, 14
	v_readlane_b32 s45, v254, 15
	v_readlane_b32 s46, v254, 16
	v_readlane_b32 s47, v254, 17
	v_readlane_b32 s48, v254, 18
	v_readlane_b32 s49, v254, 19
	v_readlane_b32 s50, v254, 20
	v_readlane_b32 s51, v254, 21
	v_lshl_add_u64 v[216:217], s[70:71], 0, v[216:217]
	s_waitcnt vmcnt(15)
	v_pk_add_f32 v[148:149], v[148:149], v[198:199]
	v_lshl_add_u64 v[214:215], v[216:217], 0, v[214:215]
	v_pk_add_f32 v[150:151], v[150:151], v[200:201]
	v_mul_f32_e32 v176, v149, v149
	global_store_dwordx4 v[214:215], v[148:151], off
	v_cvt_pk_bf16_f32 v198, v148, v149
	v_lshlrev_b64 v[200:201], 11, v[180:181]
	v_cvt_pk_bf16_f32 v199, v150, v151
	v_lshl_add_u64 v[200:201], s[6:7], 0, v[200:201]
	v_pk_fma_f32 v[148:149], v[148:149], v[148:149], v[176:177] op_sel_hi:[1,1,0]
	v_lshl_add_u64 v[200:201], v[178:179], 1, v[200:201]
	v_pk_fma_f32 v[148:149], v[150:151], v[150:151], v[148:149]
	v_mul_f32_e32 v150, v151, v151
	v_pk_add_f32 v[148:149], v[150:151], v[148:149] op_sel_hi:[0,1]
	s_waitcnt vmcnt(15)
	v_pk_add_f32 v[146:147], v[146:147], v[204:205]
	v_pk_add_f32 v[144:145], v[144:145], v[202:203]
	global_store_dwordx2 v[200:201], v[198:199], off
	v_cvt_pk_bf16_f32 v150, v144, v145
	global_store_dwordx4 v[214:215], v[144:147], off offset:64
	v_cvt_pk_bf16_f32 v151, v146, v147
	global_store_dwordx2 v[200:201], v[150:151], off offset:32
	v_mul_f32_e32 v150, v145, v145
	v_pk_fma_f32 v[144:145], v[144:145], v[144:145], v[150:151] op_sel_hi:[1,1,0]
	s_waitcnt vmcnt(17)
	v_pk_add_f32 v[142:143], v[142:143], v[208:209]
	v_pk_fma_f32 v[144:145], v[146:147], v[146:147], v[144:145]
	v_mul_f32_e32 v146, v147, v147
	v_pk_add_f32 v[144:145], v[146:147], v[144:145] op_sel_hi:[0,1]
	v_pk_add_f32 v[140:141], v[140:141], v[206:207]
	global_store_dwordx4 v[214:215], v[140:143], off offset:128
	v_cvt_pk_bf16_f32 v146, v140, v141
	v_cvt_pk_bf16_f32 v147, v142, v143
	global_store_dwordx2 v[200:201], v[146:147], off offset:64
	v_mul_f32_e32 v146, v141, v141
	v_pk_fma_f32 v[140:141], v[140:141], v[140:141], v[146:147] op_sel_hi:[1,1,0]
	s_waitcnt vmcnt(18)
	v_pk_add_f32 v[138:139], v[138:139], v[212:213]
	v_pk_fma_f32 v[140:141], v[142:143], v[142:143], v[140:141]
	v_mul_f32_e32 v142, v143, v143
	v_pk_add_f32 v[140:141], v[142:143], v[140:141] op_sel_hi:[0,1]
	v_pk_add_f32 v[136:137], v[136:137], v[210:211]
	global_store_dwordx4 v[214:215], v[136:139], off offset:192
	v_cvt_pk_bf16_f32 v142, v136, v137
	v_cvt_pk_bf16_f32 v143, v138, v139
	global_store_dwordx2 v[200:201], v[142:143], off offset:96
	v_mul_f32_e32 v142, v137, v137
	v_pk_fma_f32 v[136:137], v[136:137], v[136:137], v[142:143] op_sel_hi:[1,1,0]
	v_pk_add_f32 v[144:145], v[148:149], v[144:145]
	v_pk_fma_f32 v[136:137], v[138:139], v[138:139], v[136:137]
	v_mul_f32_e32 v138, v139, v139
	v_pk_add_f32 v[140:141], v[144:145], v[140:141]
	v_pk_add_f32 v[136:137], v[138:139], v[136:137] op_sel_hi:[0,1]
	v_pk_add_f32 v[136:137], v[140:141], v[136:137]
	s_nop 0
	v_mov_b32_e32 v137, v136
	s_nop 1
	v_permlane32_swap_b32_e32 v136, v137
	v_add_f32_e32 v136, v136, v137
	v_mov_b32_e32 v137, v136
	s_nop 1
	v_permlane16_swap_b32_e32 v136, v137
	s_and_saveexec_b64 s[24:25], vcc
	s_cbranch_execz .LBB0_564
	v_lshl_add_u64 v[138:139], v[180:181], 2, s[10:11]
	v_add_f32_e32 v136, v136, v137
	global_atomic_add_f32 v[138:139], v136, off

.LBB0_1794:
	s_ashr_i32 s0, s25, 3
	s_lshr_b32 s1, s0, 29
	s_add_i32 s1, s0, s1
	s_and_b32 s18, s1, 0x1fffff8
	s_sub_i32 s0, s0, s18
	s_lshl_b32 s1, s1, 8
	s_lshl_b32 s18, s25, 8
	s_and_b32 s1, s1, 0xfffff800
	s_and_b32 s18, s18, 0x700
	s_or_b32 s20, s1, s18
	s_ashr_i32 s21, s20, 31
	s_lshl_b32 s0, s0, 7
	s_lshl_b64 s[26:27], s[20:21], 12
	s_add_u32 s26, s3, s26
	s_addc_u32 s27, s4, s27
	s_ashr_i32 s1, s0, 31
	v_mov_b32_e32 v36, v220
	s_lshl_b64 s[28:29], s[0:1], 12
	s_add_u32 s28, s5, s28
	v_ashrrev_i32_e32 v26, 2, v36
	v_ashrrev_i32_e32 v27, 31, v26
	s_addc_u32 s29, s6, s29
	v_lshlrev_b64 v[0:1], 12, v[26:27]
	v_lshlrev_b32_e32 v4, 4, v36
	v_lshl_add_u64 v[2:3], s[28:29], 0, v[0:1]
	v_lshl_add_u64 v[0:1], s[26:27], 0, v[0:1]
	v_and_b32_e32 v176, 48, v4
	s_waitcnt vmcnt(9)
	v_lshl_add_u64 v[152:153], v[0:1], 0, v[176:177]
	v_add_co_u32_e32 v28, vcc, s7, v152
	v_lshl_add_u64 v[154:155], v[2:3], 0, v[176:177]
	s_nop 0
	v_addc_co_u32_e32 v29, vcc, 0, v153, vcc
	v_add_co_u32_e32 v30, vcc, s22, v152
	global_load_dwordx4 v[2:5], v[152:153], off
	s_nop 0
	v_addc_co_u32_e32 v31, vcc, 0, v153, vcc
	v_add_co_u32_e32 v32, vcc, s23, v152
	global_load_dwordx4 v[6:9], v[28:29], off
	s_nop 0
	v_addc_co_u32_e32 v33, vcc, 0, v153, vcc
	v_add_co_u32_e32 v34, vcc, s7, v154
	global_load_dwordx4 v[10:13], v[30:31], off
	s_nop 0
	v_addc_co_u32_e32 v35, vcc, 0, v155, vcc
	global_load_dwordx4 v[14:17], v[32:33], off
	global_load_dwordx4 v[18:21], v[154:155], off
	global_load_dwordx4 v[22:25], v[34:35], off
	global_load_dwordx4 v[112:115], v[152:153], off offset:64
	global_load_dwordx4 v[120:123], v[28:29], off offset:64
	global_load_dwordx4 v[124:127], v[30:31], off offset:64
	global_load_dwordx4 v[132:135], v[32:33], off offset:64
	global_load_dwordx4 v[128:131], v[154:155], off offset:64
	global_load_dwordx4 v[136:139], v[34:35], off offset:64
	v_lshrrev_b32_e32 v27, 4, v36
	v_lshrrev_b32_e32 v37, 2, v36
	v_sub_u32_e32 v40, 0, v27
	v_sub_u32_e32 v37, 0, v37
	v_and_b32_e32 v38, 0x3ffff8f, v36
	v_lshlrev_b32_e32 v39, 6, v36
	v_xor_b32_e32 v36, v36, v40
	v_xor_b32_e32 v27, v27, v37
	v_lshlrev_b32_e32 v36, 4, v36
	v_lshlrev_b32_e32 v27, 4, v27
	v_and_b32_e32 v41, 0x1000, v39
	v_and_b32_e32 v36, 48, v36
	v_and_b32_e32 v27, 48, v27
	v_and_b32_e32 v42, 0x3c0, v39
	v_and_b32_e32 v39, 0xffffe3c0, v39
	v_lshl_add_u32 v38, v38, 6, v198
	v_lshl_or_b32 v164, v26, 6, v36
	v_or_b32_e32 v26, v27, v41
	s_mov_b32 s1, -2
	s_mov_b32 s21, s19
	v_mov_b32_e32 v0, 0
	v_mov_b32_e32 v1, v177
	v_or3_b32 v165, v41, v42, v27
	v_add_u32_e32 v166, v27, v39
	v_add_u32_e32 v167, v27, v38
	v_add_u32_e32 v168, v26, v42
	v_lshl_add_u64 v[156:157], v[152:153], 0, s[12:13]
	v_lshl_add_u64 v[158:159], v[152:153], 0, s[14:15]
	v_lshl_add_u64 v[160:161], v[152:153], 0, s[16:17]
	v_lshl_add_u64 v[162:163], v[154:155], 0, s[12:13]
	v_mov_b32_e32 v26, v177
	v_mov_b32_e32 v27, v177
	v_mov_b32_e32 v28, 0
	v_mov_b32_e32 v29, v177
	v_mov_b32_e32 v30, v177
	v_mov_b32_e32 v31, v177
	v_mov_b32_e32 v32, 0
	v_mov_b32_e32 v33, v177
	v_mov_b32_e32 v34, v177
	v_mov_b32_e32 v35, v177
	v_mov_b32_e32 v36, 0
	v_mov_b32_e32 v37, v177
	v_mov_b32_e32 v38, v177
	v_mov_b32_e32 v39, v177
	v_mov_b32_e32 v40, 0
	v_mov_b32_e32 v41, v177
	v_mov_b32_e32 v42, v177
	v_mov_b32_e32 v43, v177
	v_mov_b32_e32 v44, 0
	s_waitcnt vmcnt(11)
	ds_write_b128 v164, v[2:5]
	s_waitcnt vmcnt(10)
	ds_write_b128 v164, v[6:9] offset:4096
	s_waitcnt vmcnt(9)
	ds_write_b128 v164, v[10:13] offset:8192
	s_waitcnt vmcnt(8)
	ds_write_b128 v164, v[14:17] offset:12288
	s_waitcnt vmcnt(7)
	ds_write_b128 v164, v[18:21] offset:32768
	s_waitcnt vmcnt(6)
	ds_write_b128 v164, v[22:25] offset:36864
	v_mov_b32_e32 v2, v177
	v_mov_b32_e32 v3, v177
	v_mov_b32_e32 v4, 0
	v_mov_b32_e32 v5, v177
	v_mov_b32_e32 v6, v177
	v_mov_b32_e32 v7, v177
	v_mov_b32_e32 v8, 0
	v_mov_b32_e32 v9, v177
	v_mov_b32_e32 v10, v177
	v_mov_b32_e32 v11, v177
	v_mov_b32_e32 v12, 0
	v_mov_b32_e32 v13, v177
	v_mov_b32_e32 v14, v177
	v_mov_b32_e32 v15, v177
	v_mov_b32_e32 v16, 0
	v_mov_b32_e32 v17, v177
	v_mov_b32_e32 v18, v177
	v_mov_b32_e32 v19, v177
	v_mov_b32_e32 v20, 0
	v_mov_b32_e32 v21, v177
	v_mov_b32_e32 v22, v177
	v_mov_b32_e32 v23, v177
	v_mov_b32_e32 v24, 0
	v_mov_b32_e32 v25, v177
	v_mov_b32_e32 v45, v177
	v_mov_b32_e32 v46, v177
	v_mov_b32_e32 v47, v177
	v_mov_b32_e32 v48, 0
	v_mov_b32_e32 v49, v177
	v_mov_b32_e32 v50, v177
	v_mov_b32_e32 v51, v177
	v_mov_b32_e32 v52, 0
	v_mov_b32_e32 v53, v177
	v_mov_b32_e32 v54, v177
	v_mov_b32_e32 v55, v177
	v_mov_b32_e32 v56, 0
	v_mov_b32_e32 v57, v177
	v_mov_b32_e32 v58, v177
	v_mov_b32_e32 v59, v177
	v_mov_b32_e32 v60, 0
	v_mov_b32_e32 v61, v177
	v_mov_b32_e32 v62, v177
	v_mov_b32_e32 v63, v177
	v_mov_b32_e32 v64, 0
	v_mov_b32_e32 v65, v177
	v_mov_b32_e32 v66, v177
	v_mov_b32_e32 v67, v177
	v_mov_b32_e32 v68, 0
	v_mov_b32_e32 v69, v177
	v_mov_b32_e32 v70, v177
	v_mov_b32_e32 v71, v177
	v_mov_b32_e32 v72, 0
	v_mov_b32_e32 v73, v177
	v_mov_b32_e32 v74, v177
	v_mov_b32_e32 v75, v177
	v_mov_b32_e32 v76, 0
	v_mov_b32_e32 v77, v177
	v_mov_b32_e32 v78, v177
	v_mov_b32_e32 v79, v177
	v_mov_b32_e32 v80, 0
	v_mov_b32_e32 v81, v177
	v_mov_b32_e32 v82, v177
	v_mov_b32_e32 v83, v177
	v_mov_b32_e32 v84, 0
	v_mov_b32_e32 v85, v177
	v_mov_b32_e32 v86, v177
	v_mov_b32_e32 v87, v177
	v_mov_b32_e32 v88, 0
	v_mov_b32_e32 v89, v177
	v_mov_b32_e32 v90, v177
	v_mov_b32_e32 v91, v177
	v_mov_b32_e32 v92, 0
	v_mov_b32_e32 v93, v177
	v_mov_b32_e32 v94, v177
	v_mov_b32_e32 v95, v177
	v_mov_b32_e32 v96, 0
	v_mov_b32_e32 v97, v177
	v_mov_b32_e32 v98, v177
	v_mov_b32_e32 v99, v177
	v_mov_b32_e32 v100, 0
	v_mov_b32_e32 v101, v177
	v_mov_b32_e32 v102, v177
	v_mov_b32_e32 v103, v177
	v_mov_b32_e32 v104, 0
	v_mov_b32_e32 v105, v177
	v_mov_b32_e32 v106, v177
	v_mov_b32_e32 v107, v177
	v_mov_b32_e32 v108, 0
	v_mov_b32_e32 v109, v177
	v_mov_b32_e32 v110, v177
	v_mov_b32_e32 v111, v177
	v_mov_b32_e32 v116, 0
	v_mov_b32_e32 v117, v177
	v_mov_b32_e32 v118, v177
	v_mov_b32_e32 v119, v177
	v_mov_b32_e32 v140, 0
	v_mov_b32_e32 v141, v177
	v_mov_b32_e32 v142, v177
	v_mov_b32_e32 v143, v177
	v_mov_b32_e32 v144, 0
	v_mov_b32_e32 v145, v177
	v_mov_b32_e32 v146, v177
	v_mov_b32_e32 v147, v177
	v_mov_b32_e32 v148, 0
	v_mov_b32_e32 v149, v177
	v_mov_b32_e32 v150, v177
	v_mov_b32_e32 v151, v177
	s_waitcnt lgkmcnt(0)
	s_add_i32 s26, s21, 64
	s_min_u32 s18, s26, 0x7e0
	s_lshl_b32 s18, s18, 1
	v_lshl_add_u64 v[178:179], v[156:157], 0, s[18:19]
	v_lshl_add_u64 v[182:183], v[158:159], 0, s[18:19]
	v_lshl_add_u64 v[170:171], v[152:153], 0, s[18:19]
	v_lshl_add_u64 v[186:187], v[160:161], 0, s[18:19]
	v_lshl_add_u64 v[190:191], v[154:155], 0, s[18:19]
	v_lshl_add_u64 v[194:195], v[162:163], 0, s[18:19]

.LBB0_1795:
	global_load_dwordx4 v[178:181], v[178:179], off
	global_load_dwordx4 v[182:185], v[182:183], off
	global_load_dwordx4 v[170:173], v[170:171], off
	ds_read_b128 v[200:203], v168 offset:32768
	global_load_dwordx4 v[186:189], v[186:187], off
	ds_read_b128 v[204:207], v168 offset:33792
	global_load_dwordx4 v[190:193], v[190:191], off
	ds_read_b128 v[208:211], v168 offset:34816
	global_load_dwordx4 v[194:197], v[194:195], off
	ds_read_b128 v[212:215], v168 offset:35840
	ds_read_b128 v[216:219], v166
	ds_read_b128 v[222:225], v166 offset:1024
	ds_read_b128 v[226:229], v166 offset:2048
	ds_read_b128 v[230:233], v166 offset:3072
	ds_read_b128 v[234:237], v166 offset:4096
	ds_read_b128 v[238:241], v166 offset:5120
	ds_read_b128 v[242:245], v166 offset:6144
	ds_read_b128 v[246:249], v166 offset:7168
	s_setprio 1
	s_waitcnt lgkmcnt(7)
	v_mfma_f32_16x16x32_bf16 v[148:151], v[200:203], v[216:219], v[148:151]
	v_mfma_f32_16x16x32_bf16 v[144:147], v[204:207], v[216:219], v[144:147]
	v_mfma_f32_16x16x32_bf16 v[140:143], v[208:211], v[216:219], v[140:143]
	v_mfma_f32_16x16x32_bf16 v[116:119], v[212:215], v[216:219], v[116:119]
	s_waitcnt vmcnt(11)
	ds_write_b128 v164, v[112:115] offset:16384
	s_waitcnt lgkmcnt(7)
	v_mfma_f32_16x16x32_bf16 v[108:111], v[200:203], v[222:225], v[108:111]
	v_mfma_f32_16x16x32_bf16 v[104:107], v[204:207], v[222:225], v[104:107]
	v_mfma_f32_16x16x32_bf16 v[100:103], v[208:211], v[222:225], v[100:103]
	v_mfma_f32_16x16x32_bf16 v[96:99], v[212:215], v[222:225], v[96:99]
	s_waitcnt vmcnt(9)
	ds_write_b128 v164, v[120:123] offset:20480
	s_waitcnt lgkmcnt(7)
	v_mfma_f32_16x16x32_bf16 v[92:95], v[200:203], v[226:229], v[92:95]
	v_mfma_f32_16x16x32_bf16 v[88:91], v[204:207], v[226:229], v[88:91]
	v_mfma_f32_16x16x32_bf16 v[84:87], v[208:211], v[226:229], v[84:87]
	v_mfma_f32_16x16x32_bf16 v[80:83], v[212:215], v[226:229], v[80:83]
	s_waitcnt vmcnt(8)
	ds_write_b128 v164, v[124:127] offset:24576
	s_waitcnt lgkmcnt(7)
	v_mfma_f32_16x16x32_bf16 v[76:79], v[200:203], v[230:233], v[76:79]
	v_mfma_f32_16x16x32_bf16 v[72:75], v[204:207], v[230:233], v[72:75]
	v_mfma_f32_16x16x32_bf16 v[68:71], v[208:211], v[230:233], v[68:71]
	v_mfma_f32_16x16x32_bf16 v[64:67], v[212:215], v[230:233], v[64:67]
	s_waitcnt vmcnt(7)
	ds_write_b128 v164, v[132:135] offset:28672
	s_waitcnt lgkmcnt(7)
	v_mfma_f32_16x16x32_bf16 v[60:63], v[200:203], v[234:237], v[60:63]
	v_mfma_f32_16x16x32_bf16 v[56:59], v[204:207], v[234:237], v[56:59]
	v_mfma_f32_16x16x32_bf16 v[52:55], v[208:211], v[234:237], v[52:55]
	v_mfma_f32_16x16x32_bf16 v[48:51], v[212:215], v[234:237], v[48:51]
	s_waitcnt vmcnt(6)
	ds_write_b128 v164, v[136:139] offset:45056
	s_waitcnt lgkmcnt(7)
	v_mfma_f32_16x16x32_bf16 v[44:47], v[200:203], v[238:241], v[44:47]
	v_mfma_f32_16x16x32_bf16 v[40:43], v[204:207], v[238:241], v[40:43]
	v_mfma_f32_16x16x32_bf16 v[36:39], v[208:211], v[238:241], v[36:39]
	v_mfma_f32_16x16x32_bf16 v[32:35], v[212:215], v[238:241], v[32:35]
	ds_write_b128 v164, v[128:131] offset:40960
	s_waitcnt lgkmcnt(7)
	v_mfma_f32_16x16x32_bf16 v[28:31], v[200:203], v[242:245], v[28:31]
	v_mfma_f32_16x16x32_bf16 v[24:27], v[204:207], v[242:245], v[24:27]
	v_mfma_f32_16x16x32_bf16 v[20:23], v[208:211], v[242:245], v[20:23]
	v_mfma_f32_16x16x32_bf16 v[16:19], v[212:215], v[242:245], v[16:19]
	s_waitcnt lgkmcnt(6)
	v_mfma_f32_16x16x32_bf16 v[12:15], v[200:203], v[246:249], v[12:15]
	v_mfma_f32_16x16x32_bf16 v[8:11], v[204:207], v[246:249], v[8:11]
	v_mfma_f32_16x16x32_bf16 v[4:7], v[208:211], v[246:249], v[4:7]
	v_mfma_f32_16x16x32_bf16 v[0:3], v[212:215], v[246:249], v[0:3]
	s_setprio 0
	s_min_u32 s18, s21, 0x780
	s_lshl_b32 s18, s18, 1
	s_mov_b32 s29, s19
	s_add_i32 s28, s18, 0xc0
	v_lshl_add_u64 v[112:113], v[152:153], 0, s[18:19]
	v_lshl_add_u64 v[120:121], v[154:155], 0, s[18:19]
	v_lshl_add_u64 v[122:123], v[156:157], 0, s[28:29]
	v_lshl_add_u64 v[124:125], v[158:159], 0, s[28:29]
	v_lshl_add_u64 v[132:133], v[160:161], 0, s[28:29]
	v_lshl_add_u64 v[136:137], v[162:163], 0, s[28:29]
	s_waitcnt lgkmcnt(0)
	s_barrier
	global_load_dwordx4 v[112:115], v[112:113], off offset:192
	ds_read_b128 v[200:203], v165 offset:40960
	global_load_dwordx4 v[128:131], v[120:121], off offset:192
	ds_read_b128 v[204:207], v165 offset:41984
	global_load_dwordx4 v[120:123], v[122:123], off
	ds_read_b128 v[208:211], v165 offset:43008
	global_load_dwordx4 v[124:127], v[124:125], off
	ds_read_b128 v[212:215], v165 offset:44032
	global_load_dwordx4 v[132:135], v[132:133], off
	ds_read_b128 v[216:219], v167
	global_load_dwordx4 v[136:139], v[136:137], off
	ds_read_b128 v[222:225], v167 offset:1024
	ds_read_b128 v[226:229], v167 offset:2048
	ds_read_b128 v[230:233], v167 offset:3072
	ds_read_b128 v[234:237], v167 offset:4096
	ds_read_b128 v[238:241], v167 offset:5120
	ds_read_b128 v[242:245], v167 offset:6144
	ds_read_b128 v[246:249], v167 offset:7168
	s_setprio 1
	s_waitcnt lgkmcnt(7)
	v_mfma_f32_16x16x32_bf16 v[148:151], v[200:203], v[216:219], v[148:151]
	v_mfma_f32_16x16x32_bf16 v[144:147], v[204:207], v[216:219], v[144:147]
	v_mfma_f32_16x16x32_bf16 v[140:143], v[208:211], v[216:219], v[140:143]
	v_mfma_f32_16x16x32_bf16 v[116:119], v[212:215], v[216:219], v[116:119]
	s_waitcnt vmcnt(9)
	ds_write_b128 v164, v[170:173]
	s_waitcnt lgkmcnt(7)
	v_mfma_f32_16x16x32_bf16 v[108:111], v[200:203], v[222:225], v[108:111]
	v_mfma_f32_16x16x32_bf16 v[104:107], v[204:207], v[222:225], v[104:107]
	v_mfma_f32_16x16x32_bf16 v[100:103], v[208:211], v[222:225], v[100:103]
	v_mfma_f32_16x16x32_bf16 v[96:99], v[212:215], v[222:225], v[96:99]
	ds_write_b128 v164, v[178:181] offset:4096
	s_waitcnt lgkmcnt(7)
	v_mfma_f32_16x16x32_bf16 v[92:95], v[200:203], v[226:229], v[92:95]
	v_mfma_f32_16x16x32_bf16 v[88:91], v[204:207], v[226:229], v[88:91]
	v_mfma_f32_16x16x32_bf16 v[84:87], v[208:211], v[226:229], v[84:87]
	v_mfma_f32_16x16x32_bf16 v[80:83], v[212:215], v[226:229], v[80:83]
	ds_write_b128 v164, v[182:185] offset:8192
	s_waitcnt lgkmcnt(7)
	v_mfma_f32_16x16x32_bf16 v[76:79], v[200:203], v[230:233], v[76:79]
	v_mfma_f32_16x16x32_bf16 v[72:75], v[204:207], v[230:233], v[72:75]
	v_mfma_f32_16x16x32_bf16 v[68:71], v[208:211], v[230:233], v[68:71]
	v_mfma_f32_16x16x32_bf16 v[64:67], v[212:215], v[230:233], v[64:67]
	s_waitcnt vmcnt(8)
	ds_write_b128 v164, v[186:189] offset:12288
	s_waitcnt lgkmcnt(7)
	v_mfma_f32_16x16x32_bf16 v[60:63], v[200:203], v[234:237], v[60:63]
	v_mfma_f32_16x16x32_bf16 v[56:59], v[204:207], v[234:237], v[56:59]
	v_mfma_f32_16x16x32_bf16 v[52:55], v[208:211], v[234:237], v[52:55]
	v_mfma_f32_16x16x32_bf16 v[48:51], v[212:215], v[234:237], v[48:51]
	s_waitcnt vmcnt(7)
	ds_write_b128 v164, v[190:193] offset:32768
	s_waitcnt lgkmcnt(7)
	v_mfma_f32_16x16x32_bf16 v[44:47], v[200:203], v[238:241], v[44:47]
	v_mfma_f32_16x16x32_bf16 v[40:43], v[204:207], v[238:241], v[40:43]
	v_mfma_f32_16x16x32_bf16 v[36:39], v[208:211], v[238:241], v[36:39]
	v_mfma_f32_16x16x32_bf16 v[32:35], v[212:215], v[238:241], v[32:35]
	s_waitcnt vmcnt(6)
	ds_write_b128 v164, v[194:197] offset:36864
	s_waitcnt lgkmcnt(7)
	v_mfma_f32_16x16x32_bf16 v[28:31], v[200:203], v[242:245], v[28:31]
	v_mfma_f32_16x16x32_bf16 v[24:27], v[204:207], v[242:245], v[24:27]
	v_mfma_f32_16x16x32_bf16 v[20:23], v[208:211], v[242:245], v[20:23]
	v_mfma_f32_16x16x32_bf16 v[16:19], v[212:215], v[242:245], v[16:19]
	s_waitcnt lgkmcnt(6)
	v_mfma_f32_16x16x32_bf16 v[12:15], v[200:203], v[246:249], v[12:15]
	v_mfma_f32_16x16x32_bf16 v[8:11], v[204:207], v[246:249], v[8:11]
	v_mfma_f32_16x16x32_bf16 v[4:7], v[208:211], v[246:249], v[4:7]
	v_mfma_f32_16x16x32_bf16 v[0:3], v[212:215], v[246:249], v[0:3]
	s_setprio 0
	s_add_i32 s1, s1, 2
	s_mov_b32 s21, s26
	s_add_i32 s26, s21, 64
	s_min_u32 s18, s26, 0x7e0
	s_lshl_b32 s18, s18, 1
	v_lshl_add_u64 v[178:179], v[156:157], 0, s[18:19]
	v_lshl_add_u64 v[182:183], v[158:159], 0, s[18:19]
	v_lshl_add_u64 v[170:171], v[152:153], 0, s[18:19]
	v_lshl_add_u64 v[186:187], v[160:161], 0, s[18:19]
	v_lshl_add_u64 v[190:191], v[154:155], 0, s[18:19]
	v_lshl_add_u64 v[194:195], v[162:163], 0, s[18:19]
	s_cmp_lt_u32 s1, 62
	s_waitcnt lgkmcnt(0)
	s_cbranch_scc1 .Lrot2_1
	s_barrier
	s_waitcnt vmcnt(5)
	v_mov_b32_e32 v112, v220
	s_nop 0
	v_and_b32_e32 v114, 0xffffff80, v112
	v_bfe_u32 v176, v112, 4, 2
	v_add_u32_e32 v114, s20, v114
	v_and_b32_e32 v113, 64, v112
	v_and_or_b32 v184, v112, 15, v114
	v_lshlrev_b32_e32 v112, 2, v176
	v_or3_b32 v178, v112, v113, s0
	v_ashrrev_i32_e32 v179, 31, v178
	v_lshlrev_b64 v[216:217], 2, v[178:179]
	v_ashrrev_i32_e32 v185, 31, v184
	v_or_b32_e32 v194, 16, v184
	v_lshl_add_u64 v[182:183], s[70:71], 0, v[216:217]
	v_lshlrev_b64 v[218:219], 12, v[184:185]
	v_ashrrev_i32_e32 v195, 31, v194
	v_or_b32_e32 v190, 32, v184
	v_lshl_add_u64 v[112:113], v[182:183], 0, v[218:219]
	v_lshlrev_b64 v[196:197], 12, v[194:195]
	v_ashrrev_i32_e32 v191, 31, v190
	v_or_b32_e32 v186, 48, v184
	global_load_dwordx4 v[200:203], v[112:113], off
	global_load_dwordx4 v[204:207], v[112:113], off offset:64
	global_load_dwordx4 v[208:211], v[112:113], off offset:128
	global_load_dwordx4 v[212:215], v[112:113], off offset:192
	v_lshl_add_u64 v[112:113], v[182:183], 0, v[196:197]
	v_lshlrev_b64 v[192:193], 12, v[190:191]
	v_ashrrev_i32_e32 v187, 31, v186
	global_load_dwordx4 v[172:175], v[112:113], off
	global_load_dwordx4 v[168:171], v[112:113], off offset:64
	global_load_dwordx4 v[164:167], v[112:113], off offset:128
	global_load_dwordx4 v[160:163], v[112:113], off offset:192
	v_lshl_add_u64 v[112:113], v[182:183], 0, v[192:193]
	v_lshlrev_b64 v[188:189], 12, v[186:187]
	global_load_dwordx4 v[156:159], v[112:113], off
	global_load_dwordx4 v[152:155], v[112:113], off offset:64
	global_load_dwordx4 v[136:139], v[112:113], off offset:128
	global_load_dwordx4 v[132:135], v[112:113], off offset:192
	v_lshl_add_u64 v[112:113], v[182:183], 0, v[188:189]
	global_load_dwordx4 v[128:131], v[112:113], off
	global_load_dwordx4 v[124:127], v[112:113], off offset:64
	global_load_dwordx4 v[120:123], v[112:113], off offset:128
	s_nop 0
	global_load_dwordx4 v[112:115], v[112:113], off offset:192
	v_cmp_eq_u32_e32 vcc, 0, v176
	v_lshlrev_b64 v[222:223], 11, v[184:185]
	v_lshlrev_b64 v[180:181], 1, v[178:179]
	v_lshl_add_u64 v[218:219], s[70:71], 0, v[218:219]
	v_lshl_add_u64 v[224:225], s[8:9], 0, v[222:223]
	v_lshl_add_u64 v[216:217], v[218:219], 0, v[216:217]
	v_lshl_add_u64 v[218:219], v[224:225], 0, v[180:181]
	v_lshl_add_u64 v[222:223], s[72:73], 0, v[222:223]
	v_lshl_add_u64 v[222:223], v[222:223], 0, v[180:181]
	s_waitcnt vmcnt(15)
	v_pk_add_f32 v[148:149], v[148:149], v[200:201]
	s_waitcnt vmcnt(14)
	v_pk_add_f32 v[144:145], v[144:145], v[204:205]
	v_pk_add_f32 v[146:147], v[146:147], v[206:207]
	s_waitcnt vmcnt(13)
	v_pk_add_f32 v[140:141], v[140:141], v[208:209]
	v_mul_f32_e32 v176, v149, v149
	v_mul_f32_e32 v206, v145, v145
	v_pk_add_f32 v[150:151], v[150:151], v[202:203]
	s_waitcnt vmcnt(12)
	v_pk_add_f32 v[116:117], v[116:117], v[212:213]
	v_mul_f32_e32 v212, v141, v141
	v_pk_fma_f32 v[226:227], v[148:149], v[148:149], v[176:177] op_sel_hi:[1,1,0]
	v_pk_fma_f32 v[206:207], v[144:145], v[144:145], v[206:207] op_sel_hi:[1,1,0]
	v_pk_add_f32 v[142:143], v[142:143], v[210:211]
	v_mul_f32_e32 v202, v151, v151
	v_mul_f32_e32 v208, v147, v147
	v_pk_fma_f32 v[212:213], v[140:141], v[140:141], v[212:213] op_sel_hi:[1,1,0]
	v_pk_fma_f32 v[226:227], v[150:151], v[150:151], v[226:227]
	v_pk_fma_f32 v[206:207], v[146:147], v[146:147], v[206:207]
	v_mul_f32_e32 v224, v143, v143
	v_pk_fma_f32 v[212:213], v[142:143], v[142:143], v[212:213]
	v_pk_add_f32 v[202:203], v[202:203], v[226:227] op_sel_hi:[0,1]
	v_pk_add_f32 v[206:207], v[208:209], v[206:207] op_sel_hi:[0,1]
	v_pk_add_f32 v[208:209], v[224:225], v[212:213] op_sel_hi:[0,1]
	v_pk_add_f32 v[202:203], v[202:203], v[206:207]
	v_cvt_pk_bf16_f32 v200, v148, v149
	v_cvt_pk_bf16_f32 v201, v150, v151
	v_cvt_pk_bf16_f32 v204, v144, v145
	v_cvt_pk_bf16_f32 v205, v146, v147
	v_cvt_pk_bf16_f32 v210, v140, v141
	v_cvt_pk_bf16_f32 v211, v142, v143
	s_nop 0
	v_pk_add_f32 v[202:203], v[202:203], v[208:209]
	v_pk_add_f32 v[118:119], v[118:119], v[214:215]
	global_store_dwordx4 v[216:217], v[148:151], off
	global_store_dwordx2 v[218:219], v[200:201], off
	global_store_dwordx4 v[216:217], v[144:147], off offset:64
	s_nop 1
	v_add_co_u32_e64 v144, s[0:1], s24, v222
	s_nop 1
	v_addc_co_u32_e64 v145, s[0:1], 0, v223, s[0:1]
	global_store_dwordx2 v[144:145], v[204:205], off offset:32
	global_store_dwordx4 v[216:217], v[140:143], off offset:128
	global_store_dwordx2 v[144:145], v[210:211], off offset:64
	global_store_dwordx4 v[216:217], v[116:119], off offset:192
	v_cvt_pk_bf16_f32 v140, v116, v117
	v_cvt_pk_bf16_f32 v141, v118, v119
	global_store_dwordx2 v[144:145], v[140:141], off offset:96
	v_mul_f32_e32 v140, v117, v117
	v_pk_fma_f32 v[116:117], v[116:117], v[116:117], v[140:141] op_sel_hi:[1,1,0]
	s_nop 0
	v_pk_fma_f32 v[116:117], v[118:119], v[118:119], v[116:117]
	v_mul_f32_e32 v118, v119, v119
	v_pk_add_f32 v[116:117], v[118:119], v[116:117] op_sel_hi:[0,1]
	v_pk_add_f32 v[116:117], v[202:203], v[116:117]
	s_nop 0
	v_mov_b32_e32 v117, v116
	s_nop 1
	v_permlane32_swap_b32_e32 v116, v117
	v_add_f32_e32 v116, v116, v117
	v_mov_b32_e32 v117, v116
	s_nop 1
	v_permlane16_swap_b32_e32 v116, v117
	s_and_saveexec_b64 s[0:1], vcc
	s_cbranch_execz .LBB0_1798
	v_lshl_add_u64 v[118:119], v[184:185], 2, s[10:11]
	v_add_f32_e32 v116, v116, v117
	global_atomic_add_f32 v[118:119], v116, off
